# A-out GEMM re-partitioned like B-out (prompt panel tile + 16 sample rows riding in the K loop, one unit per workgroup, no second round); deferred phase-0 work now on all 256 workgroups after their uni
# speedup vs baseline: 1.0338x; 1.0066x over previous
.Lp0_skipzero:
	v_ashrrev_i32_e32 v8, 6, v2
	s_lshl_b32 s0, s2, 3
	v_and_b32_e32 v47, 63, v2
	v_writelane_b32 v255, s0, 0
	v_add_u32_e32 v51, s0, v8
	s_movk_i32 s0, 0x3800
	s_lshl_b32 s33, s52, 3
	s_cmp_eq_u32 s98, 1
	s_cselect_b32 s0, s0, 0x1400
	s_cselect_b32 s33, s33, s33
	s_cselect_b32 s60, 0x1400, 0
	v_add_u32_e32 v51, s60, v51
	v_cmp_gt_i32_e32 vcc, s0, v51
	v_lshlrev_b32_e32 v18, 3, v47
	s_and_saveexec_b64 s[28:29], vcc
	s_cbranch_execz .LBB0_34
	v_lshrrev_b32_e32 v19, 5, v47
	v_and_b32_e32 v26, 31, v2
	s_movk_i32 s0, 0x84
	v_mov_b32_e32 v2, 0x630
	v_mad_u32_u24 v35, v19, s0, v2
	v_mov_b32_e32 v2, 0xc60
	v_mad_u32_u24 v42, v19, s0, v2
	v_mov_b32_e32 v2, 0x1290
	v_mad_u32_u24 v53, v19, s0, v2
	v_mov_b32_e32 v2, 0x18c0
	v_mad_u32_u24 v60, v19, s0, v2
	v_and_b32_e32 v2, 56, v18
	v_lshrrev_b32_e32 v68, 3, v47
	v_mul_u32_u24_e32 v9, 0x84, v2
	v_lshlrev_b32_e32 v2, 1, v2
	v_mov_b32_e32 v3, 0
	v_lshl_add_u32 v7, v8, 14, 0
	s_waitcnt lgkmcnt(0)
	v_lshl_add_u64 v[4:5], s[22:23], 0, v[2:3]
	v_lshlrev_b32_e32 v2, 2, v68
	v_add3_u32 v69, v7, v9, v2
	v_lshlrev_b32_e32 v2, 5, v8
	v_lshl_add_u32 v74, s2, 8, v2
	v_lshlrev_b32_e32 v2, 7, v8
	v_lshlrev_b32_e32 v6, 2, v26
	v_lshl_add_u32 v75, s2, 10, v2
	v_lshlrev_b32_e32 v2, 6, v8
	v_add_u32_e32 v27, v7, v6
	v_mov_b32_e32 v7, v3
	v_lshl_add_u32 v76, s2, 9, v2
	v_lshlrev_b32_e32 v2, 1, v8
	s_mov_b64 s[36:37], 0x3600000
	s_mov_b64 s[38:39], 0x2d00000
	s_mov_b64 s[40:41], 0x2500000
	s_mov_b64 s[42:43], 0x1c00000
	s_mov_b64 s[44:45], 0x1400000
	s_mov_b64 s[46:47], 0x1000000
	v_lshl_add_u64 v[6:7], s[30:31], 0, v[6:7]
	s_add_u32 s30, s24, 0x1000
	v_lshl_add_u32 v2, s2, 4, v2
	v_mul_u32_u24_e32 v28, 0x84, v19
	v_or_b32_e32 v29, 2, v19
	v_or_b32_e32 v30, 4, v19
	v_or_b32_e32 v31, 6, v19
	v_or_b32_e32 v32, 8, v19
	v_or_b32_e32 v33, 10, v19
	v_or_b32_e32 v34, 12, v19
	v_or_b32_e32 v36, 14, v19
	v_or_b32_e32 v37, 16, v19
	v_or_b32_e32 v38, 18, v19
	v_or_b32_e32 v39, 20, v19
	v_or_b32_e32 v40, 22, v19
	v_or_b32_e32 v41, 24, v19
	v_or_b32_e32 v43, 26, v19
	v_or_b32_e32 v46, 28, v19
	v_or_b32_e32 v48, 30, v19
	v_or_b32_e32 v49, 32, v19
	v_or_b32_e32 v50, 34, v19
	v_or_b32_e32 v52, 36, v19
	v_or_b32_e32 v54, 38, v19
	v_or_b32_e32 v55, 40, v19
	v_or_b32_e32 v56, 42, v19
	v_or_b32_e32 v57, 44, v19
	v_or_b32_e32 v58, 46, v19
	v_or_b32_e32 v59, 48, v19
	v_or_b32_e32 v61, 50, v19
	v_or_b32_e32 v62, 52, v19
	v_or_b32_e32 v63, 54, v19
	v_or_b32_e32 v64, 56, v19
	v_or_b32_e32 v65, 58, v19
	v_or_b32_e32 v66, 60, v19
	v_or_b32_e32 v67, 62, v19
	v_or_b32_e32 v70, 8, v68
	v_or_b32_e32 v71, 16, v68
	v_or_b32_e32 v72, 24, v68
	v_bitop3_b32 v73, v68, 15, 24 bitop3:0xc8
	s_addc_u32 s31, s25, 0
	s_lshl_b32 s0, s33, 5
	s_lshl_b32 s1, s33, 7
	s_lshl_b32 s3, s33, 6
	v_add_u32_e32 v77, 0x19800, v2
	s_lshl_b32 s48, s33, 1
	s_mov_b64 s[34:35], 0
	s_movk_i32 s49, 0xfff
	s_movk_i32 s50, 0x13ff
	s_movk_i32 s51, 0x1bff
	s_movk_i32 s53, 0x23ff
	s_movk_i32 s54, 0x2bff
	s_movk_i32 s55, 0x33ff
	s_movk_i32 s56, 0x7fff
	s_mov_b32 s57, 0xffff0000
	s_movk_i32 s58, 0x37ff
	v_mov_b32_e32 v78, v51
	v_lshl_add_u64 v[8:9], v[4:5], 0, s[36:37]
	v_lshl_add_u64 v[10:11], v[4:5], 0, s[38:39]
	v_lshl_add_u64 v[12:13], v[4:5], 0, s[40:41]
	v_lshl_add_u64 v[14:15], v[4:5], 0, s[42:43]
	v_lshl_add_u64 v[16:17], v[4:5], 0, s[44:45]
	v_lshl_add_u64 v[20:21], v[4:5], 0, s[46:47]
	s_cmp_eq_u32 s98, 1
	s_cselect_b32 s58, s58, 0x13ff
	s_cselect_b32 s60, 0x28000, 0
	s_cselect_b32 s61, 0xa0000, 0
	v_add_u32_e32 v74, s60, v74
	v_add_u32_e32 v75, s61, v75
	s_cselect_b32 s60, 0x50000, 0
	s_cselect_b32 s61, 0x2800, 0
	v_add_u32_e32 v76, s60, v76
	v_add_u32_e32 v77, s61, v77
	s_branch .LBB0_10

.LBB0_276:
	s_or_b64 exec, exec, s[36:37]
	s_mov_b64 s[0:1], s[96:97]
	s_waitcnt lgkmcnt(0)
	s_barrier
	s_load_dwordx2 s[6:7], s[0:1], 0xc0
	s_load_dwordx4 s[12:15], s[0:1], 0x0
	s_load_dwordx2 s[4:5], s[0:1], 0x50
	v_mov_b64_e32 v[12:13], 0x100
	v_mov_b64_e32 v[14:15], 0xff
	s_waitcnt lgkmcnt(0)
	s_add_u32 s10, s6, 0x10752000
	s_addc_u32 s11, s7, 0
	s_ashr_i32 s53, s52, 31
	s_ashr_i32 s3, s2, 31
	s_add_u32 s8, s6, 0x7f52000
	s_addc_u32 s9, s7, 0
	s_add_u32 s16, s6, 0xc352000
	s_addc_u32 s17, s7, 0
	s_add_u32 s18, s4, 0x2000
	s_addc_u32 s19, s5, 0
	s_add_u32 s20, s4, 0x4000
	s_addc_u32 s21, s5, 0
	s_movk_i32 s0, 0x7fff
	v_mov_b32_e32 v34, 1
	s_mov_b64 s[22:23], s[2:3]
	s_branch .LBB0_280

.LBB0_283:
	s_and_b32 s1, s2, 7
	s_lshl_b32 s1, s1, 3
	s_lshr_b32 s26, s2, 5
	s_add_i32 s1, s1, s26
	s_cmp_gt_i32 s1, 63
	s_cbranch_scc1 .LBB0_278
	v_mov_b32_e32 v0, v201
	s_lshl_b32 s24, s1, 8
	v_lshlrev_b32_e32 v16, 2, v0
	v_ashrrev_i32_e32 v17, 31, v16
	v_lshlrev_b64 v[4:5], 2, v[16:17]
	v_lshl_add_u64 v[0:1], s[4:5], 0, v[4:5]
	v_lshl_add_u64 v[18:19], s[18:19], 0, v[4:5]
	flat_load_dwordx4 v[0:3], v[0:1]
	v_lshl_add_u64 v[20:21], s[20:21], 0, v[4:5]
	flat_load_dwordx4 v[4:7], v[18:19]
	flat_load_dwordx4 v[8:11], v[20:21]
	v_lshlrev_b64 v[16:17], 1, v[16:17]
	s_and_b32 s25, s1, 7
	v_lshl_add_u64 v[20:21], s[8:9], 0, v[16:17]
	v_lshl_add_u64 v[18:19], s[16:17], 0, v[16:17]
	s_cmp_lg_u32 s25, 0
	v_lshl_add_u64 v[16:17], s[10:11], 0, v[16:17]
	s_cbranch_scc0 .LBB0_286
	s_ashr_i32 s25, s24, 31
	s_lshl_b64 s[26:27], s[24:25], 12
	v_lshl_add_u64 v[22:23], v[20:21], 0, s[26:27]
	v_add_co_u32_e32 v24, vcc, 0xffffe000, v22
	s_or_b32 s28, s24, 1
	s_ashr_i32 s29, s28, 31
	v_addc_co_u32_e32 v25, vcc, -1, v23, vcc
	s_lshl_b64 s[28:29], s[28:29], 12
	v_add_co_u32_e32 v30, vcc, 0xfffff000, v22
	v_lshl_add_u64 v[26:27], v[18:19], 0, s[26:27]
	v_lshl_add_u64 v[28:29], v[18:19], 0, s[28:29]
	v_addc_co_u32_e32 v31, vcc, -1, v23, vcc
	v_lshl_add_u64 v[32:33], v[20:21], 0, s[28:29]
	flat_load_dwordx2 v[26:27], v[26:27]
	s_waitcnt vmcnt(0) lgkmcnt(0)
	v_mov_b32_e32 v44, v5
	flat_load_dwordx2 v[28:29], v[28:29]
	v_mov_b32_e32 v45, v7
	flat_load_dwordx2 v[30:31], v[30:31]
	v_mov_b32_e32 v42, v1
	flat_load_dwordx2 v[24:25], v[24:25]
	s_nop 0
	flat_load_dwordx2 v[36:37], v[32:33]
	flat_load_dwordx2 v[38:39], v[22:23]
	v_mov_b32_e32 v32, v4
	v_mov_b32_e32 v33, v6
	v_mov_b32_e32 v43, v3
	v_mov_b32_e32 v22, v0
	v_mov_b32_e32 v23, v2
	v_mov_b32_e32 v46, v9
	v_mov_b32_e32 v47, v11
	v_mov_b32_e32 v40, v8
	v_mov_b32_e32 v41, v10
	v_lshlrev_b32_e32 v49, 16, v27
	v_lshlrev_b32_e32 v48, 16, v26
	v_and_b32_e32 v27, 0xffff0000, v27
	v_and_b32_e32 v26, 0xffff0000, v26
	s_waitcnt vmcnt(0) lgkmcnt(0)
	v_lshlrev_b32_e32 v55, 16, v31
	v_lshlrev_b32_e32 v54, 16, v30
	v_and_b32_e32 v31, 0xffff0000, v31
	v_and_b32_e32 v30, 0xffff0000, v30
	v_lshlrev_b32_e32 v57, 16, v39
	v_lshlrev_b32_e32 v56, 16, v38
	v_and_b32_e32 v39, 0xffff0000, v39
	v_and_b32_e32 v38, 0xffff0000, v38
	v_lshlrev_b32_e32 v53, 16, v25
	v_lshlrev_b32_e32 v52, 16, v24
	v_and_b32_e32 v25, 0xffff0000, v25
	v_and_b32_e32 v24, 0xffff0000, v24
	v_pk_mul_f32 v[62:63], v[44:45], v[38:39]
	v_pk_mul_f32 v[44:45], v[44:45], v[30:31]
	v_pk_mul_f32 v[60:61], v[32:33], v[56:57]
	v_pk_mul_f32 v[32:33], v[32:33], v[54:55]
	v_pk_fma_f32 v[24:25], v[42:43], v[24:25], v[44:45]
	v_lshlrev_b32_e32 v59, 16, v37
	v_lshlrev_b32_e32 v58, 16, v36
	v_and_b32_e32 v37, 0xffff0000, v37
	v_and_b32_e32 v36, 0xffff0000, v36
	v_pk_fma_f32 v[54:55], v[22:23], v[54:55], v[60:61]
	v_pk_fma_f32 v[30:31], v[42:43], v[30:31], v[62:63]
	v_pk_fma_f32 v[22:23], v[22:23], v[52:53], v[32:33]
	v_pk_fma_f32 v[24:25], v[46:47], v[38:39], v[24:25]
	v_lshlrev_b32_e32 v51, 16, v29
	v_lshlrev_b32_e32 v50, 16, v28
	v_and_b32_e32 v29, 0xffff0000, v29
	v_and_b32_e32 v28, 0xffff0000, v28
	v_pk_fma_f32 v[30:31], v[46:47], v[36:37], v[30:31]
	v_pk_fma_f32 v[22:23], v[40:41], v[56:57], v[22:23]
	v_pk_mul_f32 v[24:25], v[24:25], v[26:27]
	v_pk_mul_f32 v[28:29], v[30:31], v[28:29]
	v_pk_mul_f32 v[22:23], v[22:23], v[48:49]
	v_and_b32_sdwa v30, v25, v34 dst_sel:DWORD dst_unused:UNUSED_PAD src0_sel:WORD_1 src1_sel:DWORD
	v_and_b32_sdwa v31, v24, v34 dst_sel:DWORD dst_unused:UNUSED_PAD src0_sel:WORD_1 src1_sel:DWORD
	v_pk_fma_f32 v[32:33], v[40:41], v[58:59], v[54:55]
	v_and_b32_sdwa v26, v23, v34 dst_sel:DWORD dst_unused:UNUSED_PAD src0_sel:WORD_1 src1_sel:DWORD
	v_and_b32_sdwa v27, v22, v34 dst_sel:DWORD dst_unused:UNUSED_PAD src0_sel:WORD_1 src1_sel:DWORD
	v_add3_u32 v25, v25, v30, s0
	v_add3_u32 v24, v24, v31, s0
	v_pk_mul_f32 v[32:33], v[32:33], v[50:51]
	v_and_b32_sdwa v37, v29, v34 dst_sel:DWORD dst_unused:UNUSED_PAD src0_sel:WORD_1 src1_sel:DWORD
	v_and_b32_sdwa v38, v28, v34 dst_sel:DWORD dst_unused:UNUSED_PAD src0_sel:WORD_1 src1_sel:DWORD
	v_add3_u32 v22, v22, v27, s0
	v_add3_u32 v23, v23, v26, s0
	v_and_b32_e32 v25, 0xffff0000, v25
	v_and_b32_e32 v24, 0xffff0000, v24
	v_and_b32_sdwa v35, v33, v34 dst_sel:DWORD dst_unused:UNUSED_PAD src0_sel:WORD_1 src1_sel:DWORD
	v_and_b32_sdwa v36, v32, v34 dst_sel:DWORD dst_unused:UNUSED_PAD src0_sel:WORD_1 src1_sel:DWORD
	v_or_b32_sdwa v23, v25, v23 dst_sel:DWORD dst_unused:UNUSED_PAD src0_sel:DWORD src1_sel:WORD_1
	v_or_b32_sdwa v22, v24, v22 dst_sel:DWORD dst_unused:UNUSED_PAD src0_sel:DWORD src1_sel:WORD_1
	v_add3_u32 v24, v29, v37, s0
	v_add3_u32 v25, v28, v38, s0
	v_add3_u32 v26, v32, v36, s0
	v_add3_u32 v27, v33, v35, s0
	v_and_b32_e32 v24, 0xffff0000, v24
	v_and_b32_e32 v28, 0xffff0000, v25
	v_or_b32_sdwa v25, v24, v27 dst_sel:DWORD dst_unused:UNUSED_PAD src0_sel:DWORD src1_sel:WORD_1
	v_or_b32_sdwa v24, v28, v26 dst_sel:DWORD dst_unused:UNUSED_PAD src0_sel:DWORD src1_sel:WORD_1
	v_lshl_add_u64 v[26:27], v[16:17], 0, s[26:27]
	flat_store_dwordx2 v[26:27], v[22:23]
	v_lshl_add_u64 v[22:23], v[16:17], 0, s[28:29]
	flat_store_dwordx2 v[22:23], v[24:25]
	v_mov_b32_e32 v23, v6
	v_mov_b32_e32 v22, v4
	v_mov_b32_e32 v25, v2
	v_mov_b32_e32 v24, v0
	v_mov_b32_e32 v29, v10
	v_mov_b32_e32 v28, v8
	v_mov_b32_e32 v27, v7
	v_mov_b32_e32 v26, v5
	v_mov_b32_e32 v31, v3
	v_mov_b32_e32 v30, v1
	v_mov_b32_e32 v33, v11
	v_mov_b32_e32 v32, v9
	s_cbranch_execnz .LBB0_277
	s_branch .LBB0_287

.LBB0_288:
	s_waitcnt vmcnt(0)
	v_mov_b32_e32 v8, v201
	s_cmpk_lt_i32 s2, 0x110
	s_waitcnt lgkmcnt(0)
	s_barrier
	s_cselect_b64 s[8:9], -1, 0
	s_cmpk_gt_i32 s2, 0x10f
	v_readfirstlane_b32 s26, v8
	s_cbranch_scc1 .LBB0_290
	s_lshr_b32 s0, s3, 29
	s_add_i32 s0, s2, s0
	s_ashr_i32 s1, s0, 3
	s_and_b32 s0, s0, -8
	s_sub_i32 s0, s2, s0
	s_cmp_lt_i32 s0, 0
	s_cselect_b32 s4, 35, 34
	s_mul_i32 s0, s0, s4
	s_add_i32 s0, s0, s1
	s_ashr_i32 s1, s0, 31
	s_lshr_b32 s1, s1, 27
	s_add_i32 s1, s0, s1
	s_ashr_i32 s1, s1, 5
	s_lshl_b32 s4, s1, 3
	s_sub_i32 s5, 0x44, s4
	s_lshl_b32 s1, s1, 5
	s_min_u32 s5, s5, 8
	s_sub_i32 s16, s0, s1
	s_sext_i32_i8 s0, s16
	v_cvt_f32_ubyte0_e32 v1, s5
	v_cvt_f32_i32_e32 v0, s0
	v_rcp_iflag_f32_e32 v2, v1
	s_ashr_i32 s0, s0, 30
	s_or_b32 s17, s0, 1
	v_mul_f32_e32 v2, v0, v2
	v_trunc_f32_e32 v2, v2
	v_fma_f32 v0, -v2, v1, v0
	v_cvt_i32_f32_e32 v2, v2
	v_cmp_ge_f32_e64 s[0:1], |v0|, v1
	s_and_b64 s[0:1], s[0:1], exec
	s_cselect_b32 s0, s17, 0
	v_readfirstlane_b32 s1, v2
	s_add_i32 s0, s1, s0
	s_sext_i32_i8 s38, s0
	s_mul_i32 s0, s0, s5
	s_sub_i32 s0, s16, s0
	s_sext_i32_i8 s0, s0
	s_add_i32 s40, s4, s0
	s_and_b32 s40, s2, 7
	s_lshr_b32 s38, s2, 3
	s_lshl_b32 s40, s40, 3
	s_lshr_b32 s0, s38, 2
	s_add_i32 s40, s40, s0
	s_and_b32 s38, s38, 3
.LBB0_290:
	v_cndmask_b32_e64 v0, 0, 1, s[8:9]
	v_cmp_ne_u32_e64 s[0:1], 1, v0
	s_andn2_b64 vcc, exec, s[8:9]
	s_nop 0
	v_writelane_b32 v255, s0, 1
	s_nop 1
	v_writelane_b32 v255, s1, 2
	s_cbranch_vccnz .LBB0_354
	v_ashrrev_i32_e32 v1, 31, v8
	v_lshrrev_b32_e32 v1, 26, v1
	v_add_u32_e32 v1, v8, v1
	v_ashrrev_i32_e32 v9, 6, v1
	v_bfe_i32 v1, v8, 27, 1
	v_lshlrev_b32_e32 v0, 4, v8
	v_lshrrev_b32_e32 v1, 22, v1
	v_add_u32_e32 v1, v0, v1
	v_and_b32_e32 v1, 0xfffffc00, v1
	v_sub_u32_e32 v1, v0, v1
	v_lshrrev_b32_e32 v2, 4, v1
	v_bitop3_b32 v2, v2, v1, 32 bitop3:0x6c
	v_ashrrev_i32_e32 v1, 31, v1
	v_lshrrev_b32_e32 v1, 26, v1
	v_add_u32_e32 v1, v2, v1
	v_ashrrev_i32_e32 v10, 6, v1
	v_mul_i32_i24_e32 v4, 64, v10
	v_sub_u32_e32 v2, v2, v4
	v_mov_b32_e32 v4, 1
	v_lshlrev_b32_e32 v3, 3, v9
	v_lshlrev_b32_e32 v1, 5, v9
	v_ashrrev_i16_sdwa v2, v4, sext(v2) dst_sel:DWORD dst_unused:UNUSED_PAD src0_sel:DWORD src1_sel:BYTE_0
	v_and_b32_e32 v3, 0xffff0, v3
	v_and_b32_e32 v1, 32, v1
	v_bfe_i32 v11, v2, 0, 16
	v_add_u32_e32 v1, v1, v11
	v_add_lshl_u32 v2, v10, v3, 12
	v_add_u32_e32 v0, 0x2000, v0
	v_lshl_add_u32 v128, v1, 1, v2
	v_ashrrev_i32_e32 v1, 31, v0
	v_lshrrev_b32_e32 v1, 22, v1
	v_add_u32_e32 v1, v0, v1
	v_ashrrev_i32_e32 v12, 10, v1
	v_mul_i32_i24_e32 v1, 0x400, v12
	v_sub_u32_e32 v0, v0, v1
	v_lshrrev_b32_e32 v1, 4, v0
	v_bitop3_b32 v0, v1, v0, 32 bitop3:0x6c
	v_ashrrev_i32_e32 v2, 31, v0
	s_add_u32 s0, s6, 0x1000000
	v_lshrrev_b32_e32 v2, 26, v2
	s_addc_u32 s1, s7, 0
	v_add_u32_e32 v2, v0, v2
	s_ashr_i32 s9, s26, 6
	s_ashr_i32 s41, s40, 31
	s_ashr_i32 s39, s38, 31
	s_ashr_i32 s8, s26, 8
	v_ashrrev_i32_e32 v13, 6, v2
	v_and_b32_e32 v2, 0xc0, v2
	s_lshl_b32 s4, s9, 10
	s_lshl_b64 s[16:17], s[40:41], 20
	s_lshl_b64 s[18:19], s[38:39], 20
	v_sub_u32_e32 v0, v0, v2
	s_add_u32 s42, s0, s18
	v_lshlrev_b32_e32 v1, 3, v12
	v_lshlrev_b32_e32 v3, 5, v12
	v_ashrrev_i16_sdwa v0, v4, sext(v0) dst_sel:DWORD dst_unused:UNUSED_PAD src0_sel:DWORD src1_sel:BYTE_0
	s_addc_u32 s43, s1, s19
	s_add_i32 s5, s4, 0
	s_lshl_b32 s66, s40, 16
	s_add_u32 s66, s66, 0x4000000
	s_add_u32 s66, s10, s66
	s_addc_u32 s67, s11, 0
	v_lshrrev_b32_e32 v209, 6, v201
	s_nop 0
	v_readfirstlane_b32 s65, v209
	s_lshl_b32 s68, s65, 8
	s_add_i32 s68, s68, 0x20000
	v_and_b32_e32 v254, 15, v200
	v_lshlrev_b32_e32 v254, 12, v254
	v_lshl_add_u32 v254, s65, 4, v254
	v_lshlrev_b32_e32 v209, 4, v200
	v_add_u32_e32 v209, 0x20000, v209
	v_mov_b32_e32 v234, 0
	v_mov_b32_e32 v235, 0
	v_mov_b32_e32 v236, 0
	v_mov_b32_e32 v237, 0
	v_mov_b32_e32 v238, 0
	v_mov_b32_e32 v239, 0
	v_mov_b32_e32 v240, 0
	v_mov_b32_e32 v241, 0
	v_mov_b32_e32 v242, 0
	v_mov_b32_e32 v243, 0
	v_mov_b32_e32 v244, 0
	v_mov_b32_e32 v245, 0
	v_mov_b32_e32 v246, 0
	v_mov_b32_e32 v247, 0
	v_mov_b32_e32 v248, 0
	v_mov_b32_e32 v249, 0
	s_mov_b32 exec_lo, 0xffff
	s_mov_b32 exec_hi, 0
	s_mov_b32 m0, s68
	s_nop 0
	global_load_lds_dwordx4 v254, s[66:67]
	s_mov_b64 exec, -1
	v_and_b32_e32 v1, 0xffff0, v1
	v_and_b32_e32 v3, 32, v3
	v_bfe_i32 v14, v0, 0, 16
	s_add_i32 m0, s5, 0x10000
	v_add_u32_e32 v0, v3, v14
	v_add_lshl_u32 v1, v13, v1, 12
	global_load_lds_dwordx4 v128, s[42:43]
	s_add_i32 m0, s5, 0x12000
	v_lshl_add_u32 v130, v0, 1, v1
	s_add_u32 s18, s42, 0x80000
	global_load_lds_dwordx4 v130, s[42:43]
	s_addc_u32 s19, s43, 0
	s_add_i32 m0, s5, 0x14000
	v_mov_b32_e32 v133, 0
	global_load_lds_dwordx4 v128, s[18:19]
	s_add_i32 m0, s5, 0x16000
	s_add_u32 s44, s10, s16
	s_addc_u32 s45, s11, s17
	s_add_i32 s48, s5, 0x2000
	global_load_lds_dwordx4 v130, s[18:19]
	s_mov_b32 m0, s5
	s_add_u32 s16, s44, 0x80000
	global_load_lds_dwordx4 v128, s[44:45]
	s_mov_b32 m0, s48
	s_addc_u32 s17, s45, 0
	s_add_i32 s49, s5, 0x4000
	global_load_lds_dwordx4 v130, s[44:45]
	s_mov_b32 m0, s49
	s_add_i32 s50, s5, 0x6000
	global_load_lds_dwordx4 v128, s[16:17]
	s_mov_b32 m0, s50
	v_mov_b32_e32 v129, v133
	global_load_lds_dwordx4 v130, s[16:17]
	v_mov_b32_e32 v131, v133
	s_cmp_eq_u32 s8, 1
	s_mov_b32 s51, 0
	v_lshl_add_u64 v[6:7], s[42:43], 0, v[128:129]
	v_lshl_add_u64 v[4:5], s[42:43], 0, v[130:131]
	v_lshl_add_u64 v[0:1], s[44:45], 0, v[128:129]
	s_cselect_b64 s[16:17], -1, 0
	s_cmp_lg_u32 s8, 1
	v_lshl_add_u64 v[2:3], s[44:45], 0, v[130:131]
	s_cbranch_scc1 .LBB0_293
	s_barrier
.LBB0_293:
	s_add_u32 s18, s6, 0x36b52000
	s_addc_u32 s19, s7, 0
	s_add_u32 s20, s6, 0x5d52000
	s_addc_u32 s21, s7, 0
	s_add_u32 s22, s6, 0x3aa8000
	s_addc_u32 s23, s7, 0
	s_lshl_b32 s6, s9, 5
	s_mov_b64 s[24:25], 0x80
	s_and_b32 s9, s6, 0x60
	s_add_i32 m0, s5, 0x18000
	v_lshl_add_u64 v[6:7], v[6:7], 0, s[24:25]
	s_lshl_b32 s27, s8, 13
	s_lshl_b32 s28, s9, 7
	s_waitcnt vmcnt(2)
	s_barrier
	s_add_u32 s70, s66, 0x80
	s_addc_u32 s71, s67, 0
	s_mov_b32 exec_lo, 0xffff
	s_mov_b32 exec_hi, 0
	s_add_i32 m0, s68, 0x800
	s_nop 0
	global_load_lds_dwordx4 v254, s[70:71]
	s_mov_b64 exec, -1
	s_add_i32 m0, s5, 0x18000
	s_nop 0
	global_load_lds_dwordx4 v[6:7], off
	v_lshl_add_u64 v[4:5], v[4:5], 0, s[24:25]
	s_add_i32 m0, s5, 0x1a000
	s_add_i32 s54, s5, 0x8000
	s_add_i32 s55, s5, 0xa000
	global_load_lds_dwordx4 v[4:5], off
	v_lshl_add_u64 v[0:1], v[0:1], 0, s[24:25]
	s_mov_b32 m0, s54
	s_add_u32 s6, s42, 0x80080
	global_load_lds_dwordx4 v[0:1], off
	v_lshl_add_u64 v[0:1], v[2:3], 0, s[24:25]
	s_mov_b32 m0, s55
	s_addc_u32 s7, s43, 0
	global_load_lds_dwordx4 v[0:1], off
	s_add_i32 m0, s5, 0x1c000
	v_lshl_add_u64 v[0:1], s[6:7], 0, v[128:129]
	global_load_lds_dwordx4 v[0:1], off
	v_lshl_add_u64 v[0:1], s[6:7], 0, v[130:131]
	s_add_i32 m0, s5, 0x1e000
	s_cmpk_lt_u32 s26, 0x100
	global_load_lds_dwordx4 v[0:1], off
	v_bfe_u32 v1, v8, 4, 2
	v_and_b32_e32 v0, 15, v8
	v_lshlrev_b32_e32 v2, 4, v1
	v_lshl_or_b32 v150, s8, 6, v0
	v_lshl_or_b32 v0, v0, 6, v2
	v_lshlrev_b32_e32 v2, 2, v8
	v_and_b32_e32 v2, 32, v2
	v_bitop3_b32 v3, v0, s27, v2 bitop3:0xde
	v_bitop3_b32 v151, v0, s28, v2 bitop3:0xde
	v_add_u32_e32 v0, 64, v208
	v_cmp_lt_i32_e32 vcc, v203, v0
	v_cmp_eq_u32_e64 s[6:7], 0, v1
	v_lshl_or_b32 v154, v1, 2, s9
	v_cndmask_b32_e32 v2, v200, v203, vcc
	v_cmp_lt_i32_e32 vcc, v202, v0
	v_and_b32_e32 v1, 1, v12
	s_waitcnt vmcnt(6)
	s_cselect_b64 s[26:27], -1, 0
	v_cndmask_b32_e32 v0, v200, v202, vcc
	v_lshlrev_b32_e32 v153, 2, v0
	v_lshlrev_b32_e32 v0, 15, v12
	v_and_b32_e32 v0, 0xffff0000, v0
	v_lshl_add_u32 v0, v13, 12, v0
	v_lshl_or_b32 v0, v1, 6, v0
	v_lshl_add_u32 v134, v14, 1, v0
	v_lshlrev_b32_e32 v0, 15, v9
	v_and_b32_e32 v0, 0xffff0000, v0
	v_lshl_add_u32 v0, v10, 12, v0
	v_and_b32_e32 v1, 1, v9
	v_lshl_or_b32 v0, v1, 6, v0
	s_add_i32 s56, 0, 0x10000
	s_add_i32 s57, 0, 0x14000
	v_lshlrev_b32_e32 v152, 2, v2
	v_mov_b32_e32 v135, v133
	v_lshl_add_u32 v136, v11, 1, v0
	v_mov_b32_e32 v137, v133
	v_mov_b64_e32 v[138:139], 0
	v_mov_b64_e32 v[140:141], 0
	v_add_u32_e32 v155, s56, v151
	v_add_u32_e32 v156, s57, v151
	v_add_u32_e32 v157, 0, v3
	s_movk_i32 s58, 0x3fff
	s_barrier
	s_branch .LBB0_296

.LBB0_299:
	ds_read_b128 v[142:145], v155
	ds_read_b128 v[146:149], v155 offset:1024
	ds_read_b128 v[158:161], v155 offset:2048
	ds_read_b128 v[162:165], v155 offset:3072
	ds_read_b128 v[166:169], v156
	ds_read_b128 v[170:173], v156 offset:1024
	ds_read_b128 v[174:177], v156 offset:2048
	ds_read_b128 v[178:181], v156 offset:3072
	s_add_u32 s44, s42, 0xfff80080
	s_addc_u32 s45, s43, -1
	s_cmp_eq_u32 s61, 28
	s_cselect_b32 s47, s31, s45
	s_cselect_b32 s46, s39, s44
	s_cselect_b32 s45, s29, s60
	s_cselect_b32 s44, s41, s59
	v_lshl_add_u64 v[198:199], s[42:43], 0, v[136:137]
	s_add_i32 m0, s5, 0xc000
	ds_read_b128 v[182:185], v157
	ds_read_b128 v[186:189], v157 offset:1024
	ds_read_b128 v[190:193], v157 offset:2048
	ds_read_b128 v[194:197], v157 offset:3072
	ds_read_b128 v[210:213], v157 offset:4096
	ds_read_b128 v[214:217], v157 offset:5120
	ds_read_b128 v[218:221], v157 offset:6144
	ds_read_b128 v[222:225], v157 offset:7168
	ds_read_b128 v[138:141], v209
	ds_read_b128 v[250:253], v209 offset:1024
	global_load_lds_dwordx4 v[198:199], off
	v_lshl_add_u64 v[198:199], s[42:43], 0, v[134:135]
	s_add_i32 m0, s5, 0xe000
	s_nop 0
	global_load_lds_dwordx4 v[198:199], off
	s_waitcnt vmcnt(9)
	s_waitcnt lgkmcnt(0)
	s_barrier
	s_setprio 1
	s_waitcnt lgkmcnt(0)
	v_mfma_f32_16x16x32_bf16 v[124:127], v[142:145], v[182:185], v[124:127]
	v_mfma_f32_16x16x32_bf16 v[120:123], v[158:161], v[182:185], v[120:123]
	v_mfma_f32_16x16x32_bf16 v[108:111], v[142:145], v[190:193], v[108:111]
	v_mfma_f32_16x16x32_bf16 v[104:107], v[158:161], v[190:193], v[104:107]
	v_mfma_f32_16x16x32_bf16 v[92:95], v[142:145], v[210:213], v[92:95]
	v_mfma_f32_16x16x32_bf16 v[88:91], v[158:161], v[210:213], v[88:91]
	v_mfma_f32_16x16x32_bf16 v[76:79], v[142:145], v[218:221], v[76:79]
	v_mfma_f32_16x16x32_bf16 v[72:75], v[158:161], v[218:221], v[72:75]
	v_mfma_f32_16x16x32_bf16 v[124:127], v[146:149], v[186:189], v[124:127]
	v_mfma_f32_16x16x32_bf16 v[120:123], v[162:165], v[186:189], v[120:123]
	v_mfma_f32_16x16x32_bf16 v[108:111], v[146:149], v[194:197], v[108:111]
	v_mfma_f32_16x16x32_bf16 v[104:107], v[162:165], v[194:197], v[104:107]
	v_mfma_f32_16x16x32_bf16 v[92:95], v[146:149], v[214:217], v[92:95]
	v_mfma_f32_16x16x32_bf16 v[88:91], v[162:165], v[214:217], v[88:91]
	v_mfma_f32_16x16x32_bf16 v[76:79], v[146:149], v[222:225], v[76:79]
	v_mfma_f32_16x16x32_bf16 v[72:75], v[162:165], v[222:225], v[72:75]
	v_mfma_f32_16x16x32_bf16 v[234:237], v[142:145], v[138:141], v[234:237]
	v_mfma_f32_16x16x32_bf16 v[238:241], v[158:161], v[138:141], v[238:241]
	v_mfma_f32_16x16x32_bf16 v[234:237], v[146:149], v[250:253], v[234:237]
	v_mfma_f32_16x16x32_bf16 v[238:241], v[162:165], v[250:253], v[238:241]
	s_setprio 0
	s_setprio 1
	v_mfma_f32_16x16x32_bf16 v[116:119], v[166:169], v[182:185], v[116:119]
	v_mfma_f32_16x16x32_bf16 v[112:115], v[174:177], v[182:185], v[112:115]
	v_mfma_f32_16x16x32_bf16 v[100:103], v[166:169], v[190:193], v[100:103]
	v_mfma_f32_16x16x32_bf16 v[96:99], v[174:177], v[190:193], v[96:99]
	v_mfma_f32_16x16x32_bf16 v[84:87], v[166:169], v[210:213], v[84:87]
	v_mfma_f32_16x16x32_bf16 v[80:83], v[174:177], v[210:213], v[80:83]
	v_mfma_f32_16x16x32_bf16 v[68:71], v[166:169], v[218:221], v[68:71]
	v_mfma_f32_16x16x32_bf16 v[64:67], v[174:177], v[218:221], v[64:67]
	v_mfma_f32_16x16x32_bf16 v[116:119], v[170:173], v[186:189], v[116:119]
	v_mfma_f32_16x16x32_bf16 v[112:115], v[178:181], v[186:189], v[112:115]
	v_mfma_f32_16x16x32_bf16 v[100:103], v[170:173], v[194:197], v[100:103]
	v_mfma_f32_16x16x32_bf16 v[96:99], v[178:181], v[194:197], v[96:99]
	v_mfma_f32_16x16x32_bf16 v[84:87], v[170:173], v[214:217], v[84:87]
	v_mfma_f32_16x16x32_bf16 v[80:83], v[178:181], v[214:217], v[80:83]
	v_mfma_f32_16x16x32_bf16 v[68:71], v[170:173], v[222:225], v[68:71]
	v_mfma_f32_16x16x32_bf16 v[64:67], v[178:181], v[222:225], v[64:67]
	v_mfma_f32_16x16x32_bf16 v[242:245], v[166:169], v[138:141], v[242:245]
	v_mfma_f32_16x16x32_bf16 v[246:249], v[174:177], v[138:141], v[246:249]
	v_mfma_f32_16x16x32_bf16 v[242:245], v[170:173], v[250:253], v[242:245]
	v_mfma_f32_16x16x32_bf16 v[246:249], v[178:181], v[250:253], v[246:249]
	s_setprio 0
	s_barrier
	s_add_u32 s70, s66, 0x100
	s_addc_u32 s71, s67, 0
	s_mov_b32 exec_lo, 0xffff
	s_mov_b32 exec_hi, 0
	s_mov_b32 m0, s68
	s_nop 0
	global_load_lds_dwordx4 v254, s[70:71]
	s_mov_b64 exec, -1
	s_add_i32 s62, s56, s4
	v_lshl_add_u64 v[198:199], s[44:45], 0, v[128:129]
	s_mov_b32 m0, s62
	ds_read_b128 v[182:185], v157 offset:16384
	ds_read_b128 v[186:189], v157 offset:17408
	ds_read_b128 v[190:193], v157 offset:18432
	ds_read_b128 v[194:197], v157 offset:19456
	ds_read_b128 v[210:213], v157 offset:20480
	ds_read_b128 v[214:217], v157 offset:21504
	ds_read_b128 v[218:221], v157 offset:22528
	ds_read_b128 v[222:225], v157 offset:23552
	global_load_lds_dwordx4 v[198:199], off
	s_add_i32 m0, s62, 0x2000
	s_add_u32 s62, s44, 0x80000
	v_lshl_add_u64 v[226:227], s[44:45], 0, v[130:131]
	s_addc_u32 s63, s45, 0
	s_add_i32 s64, s57, s4
	global_load_lds_dwordx4 v[226:227], off
	v_lshl_add_u64 v[228:229], s[62:63], 0, v[128:129]
	s_mov_b32 m0, s64
	v_lshl_add_u64 v[230:231], s[46:47], 0, v[130:131]
	global_load_lds_dwordx4 v[228:229], off
	v_lshl_add_u64 v[228:229], s[62:63], 0, v[130:131]
	s_add_i32 m0, s64, 0x2000
	s_nop 0
	global_load_lds_dwordx4 v[228:229], off
	v_lshl_add_u64 v[228:229], s[46:47], 0, v[128:129]
	s_mov_b32 m0, s5
	s_nop 0
	global_load_lds_dwordx4 v[228:229], off
	s_mov_b32 m0, s48
	s_nop 0
	global_load_lds_dwordx4 v[230:231], off
	s_waitcnt vmcnt(9)
	s_waitcnt lgkmcnt(0)
	s_barrier
	s_setprio 1
	s_waitcnt lgkmcnt(0)
	v_mfma_f32_16x16x32_bf16 v[60:63], v[142:145], v[182:185], v[60:63]
	v_mfma_f32_16x16x32_bf16 v[56:59], v[158:161], v[182:185], v[56:59]
	v_mfma_f32_16x16x32_bf16 v[44:47], v[142:145], v[190:193], v[44:47]
	v_mfma_f32_16x16x32_bf16 v[40:43], v[158:161], v[190:193], v[40:43]
	v_mfma_f32_16x16x32_bf16 v[28:31], v[142:145], v[210:213], v[28:31]
	v_mfma_f32_16x16x32_bf16 v[24:27], v[158:161], v[210:213], v[24:27]
	v_mfma_f32_16x16x32_bf16 v[12:15], v[142:145], v[218:221], v[12:15]
	v_mfma_f32_16x16x32_bf16 v[8:11], v[158:161], v[218:221], v[8:11]
	v_mfma_f32_16x16x32_bf16 v[60:63], v[146:149], v[186:189], v[60:63]
	v_mfma_f32_16x16x32_bf16 v[56:59], v[162:165], v[186:189], v[56:59]
	v_mfma_f32_16x16x32_bf16 v[44:47], v[146:149], v[194:197], v[44:47]
	v_mfma_f32_16x16x32_bf16 v[40:43], v[162:165], v[194:197], v[40:43]
	v_mfma_f32_16x16x32_bf16 v[28:31], v[146:149], v[214:217], v[28:31]
	v_mfma_f32_16x16x32_bf16 v[24:27], v[162:165], v[214:217], v[24:27]
	v_mfma_f32_16x16x32_bf16 v[12:15], v[146:149], v[222:225], v[12:15]
	v_mfma_f32_16x16x32_bf16 v[8:11], v[162:165], v[222:225], v[8:11]
	s_setprio 0
	s_setprio 1
	v_mfma_f32_16x16x32_bf16 v[52:55], v[166:169], v[182:185], v[52:55]
	v_mfma_f32_16x16x32_bf16 v[48:51], v[174:177], v[182:185], v[48:51]
	v_mfma_f32_16x16x32_bf16 v[36:39], v[166:169], v[190:193], v[36:39]
	v_mfma_f32_16x16x32_bf16 v[32:35], v[174:177], v[190:193], v[32:35]
	v_mfma_f32_16x16x32_bf16 v[20:23], v[166:169], v[210:213], v[20:23]
	v_mfma_f32_16x16x32_bf16 v[16:19], v[174:177], v[210:213], v[16:19]
	v_mfma_f32_16x16x32_bf16 v[4:7], v[166:169], v[218:221], v[4:7]
	v_mfma_f32_16x16x32_bf16 v[0:3], v[174:177], v[218:221], v[0:3]
	v_mfma_f32_16x16x32_bf16 v[52:55], v[170:173], v[186:189], v[52:55]
	v_mfma_f32_16x16x32_bf16 v[48:51], v[178:181], v[186:189], v[48:51]
	v_mfma_f32_16x16x32_bf16 v[36:39], v[170:173], v[194:197], v[36:39]
	v_mfma_f32_16x16x32_bf16 v[32:35], v[178:181], v[194:197], v[32:35]
	v_mfma_f32_16x16x32_bf16 v[20:23], v[170:173], v[214:217], v[20:23]
	v_mfma_f32_16x16x32_bf16 v[16:19], v[178:181], v[214:217], v[16:19]
	v_mfma_f32_16x16x32_bf16 v[4:7], v[170:173], v[222:225], v[4:7]
	v_mfma_f32_16x16x32_bf16 v[0:3], v[178:181], v[222:225], v[0:3]
	s_setprio 0
	s_barrier
	s_add_i32 s62, 0, 0x18000
	v_add_u32_e32 v132, s62, v151
	s_add_i32 s63, 0, 0x1c000
	ds_read_b128 v[142:145], v132
	ds_read_b128 v[146:149], v132 offset:1024
	ds_read_b128 v[158:161], v132 offset:2048
	ds_read_b128 v[162:165], v132 offset:3072
	v_add_u32_e32 v132, s63, v151
	ds_read_b128 v[166:169], v132
	ds_read_b128 v[170:173], v132 offset:1024
	ds_read_b128 v[174:177], v132 offset:2048
	ds_read_b128 v[178:181], v132 offset:3072
	s_add_u32 s46, s46, 0x80000
	s_addc_u32 s47, s47, 0
	s_mov_b32 m0, s49
	v_lshl_add_u64 v[232:233], s[46:47], 0, v[128:129]
	ds_read_b128 v[182:185], v157 offset:32768
	ds_read_b128 v[186:189], v157 offset:33792
	ds_read_b128 v[190:193], v157 offset:34816
	ds_read_b128 v[194:197], v157 offset:35840
	ds_read_b128 v[210:213], v157 offset:36864
	ds_read_b128 v[214:217], v157 offset:37888
	ds_read_b128 v[218:221], v157 offset:38912
	ds_read_b128 v[222:225], v157 offset:39936
	ds_read_b128 v[138:141], v209 offset:2048
	ds_read_b128 v[250:253], v209 offset:3072
	global_load_lds_dwordx4 v[232:233], off
	v_lshl_add_u64 v[232:233], s[46:47], 0, v[130:131]
	s_mov_b32 m0, s50
	s_nop 0
	global_load_lds_dwordx4 v[232:233], off
	s_waitcnt vmcnt(9)
	s_waitcnt lgkmcnt(0)
	s_barrier
	s_setprio 1
	s_waitcnt lgkmcnt(0)
	v_mfma_f32_16x16x32_bf16 v[124:127], v[142:145], v[182:185], v[124:127]
	v_mfma_f32_16x16x32_bf16 v[120:123], v[158:161], v[182:185], v[120:123]
	v_mfma_f32_16x16x32_bf16 v[108:111], v[142:145], v[190:193], v[108:111]
	v_mfma_f32_16x16x32_bf16 v[104:107], v[158:161], v[190:193], v[104:107]
	v_mfma_f32_16x16x32_bf16 v[92:95], v[142:145], v[210:213], v[92:95]
	v_mfma_f32_16x16x32_bf16 v[88:91], v[158:161], v[210:213], v[88:91]
	v_mfma_f32_16x16x32_bf16 v[76:79], v[142:145], v[218:221], v[76:79]
	v_mfma_f32_16x16x32_bf16 v[72:75], v[158:161], v[218:221], v[72:75]
	v_mfma_f32_16x16x32_bf16 v[124:127], v[146:149], v[186:189], v[124:127]
	v_mfma_f32_16x16x32_bf16 v[120:123], v[162:165], v[186:189], v[120:123]
	v_mfma_f32_16x16x32_bf16 v[108:111], v[146:149], v[194:197], v[108:111]
	v_mfma_f32_16x16x32_bf16 v[104:107], v[162:165], v[194:197], v[104:107]
	v_mfma_f32_16x16x32_bf16 v[92:95], v[146:149], v[214:217], v[92:95]
	v_mfma_f32_16x16x32_bf16 v[88:91], v[162:165], v[214:217], v[88:91]
	v_mfma_f32_16x16x32_bf16 v[76:79], v[146:149], v[222:225], v[76:79]
	v_mfma_f32_16x16x32_bf16 v[72:75], v[162:165], v[222:225], v[72:75]
	v_mfma_f32_16x16x32_bf16 v[234:237], v[142:145], v[138:141], v[234:237]
	v_mfma_f32_16x16x32_bf16 v[238:241], v[158:161], v[138:141], v[238:241]
	v_mfma_f32_16x16x32_bf16 v[234:237], v[146:149], v[250:253], v[234:237]
	v_mfma_f32_16x16x32_bf16 v[238:241], v[162:165], v[250:253], v[238:241]
	s_setprio 0
	s_setprio 1
	v_mfma_f32_16x16x32_bf16 v[116:119], v[166:169], v[182:185], v[116:119]
	v_mfma_f32_16x16x32_bf16 v[112:115], v[174:177], v[182:185], v[112:115]
	v_mfma_f32_16x16x32_bf16 v[100:103], v[166:169], v[190:193], v[100:103]
	v_mfma_f32_16x16x32_bf16 v[96:99], v[174:177], v[190:193], v[96:99]
	v_mfma_f32_16x16x32_bf16 v[84:87], v[166:169], v[210:213], v[84:87]
	v_mfma_f32_16x16x32_bf16 v[80:83], v[174:177], v[210:213], v[80:83]
	v_mfma_f32_16x16x32_bf16 v[68:71], v[166:169], v[218:221], v[68:71]
	v_mfma_f32_16x16x32_bf16 v[64:67], v[174:177], v[218:221], v[64:67]
	v_mfma_f32_16x16x32_bf16 v[116:119], v[170:173], v[186:189], v[116:119]
	v_mfma_f32_16x16x32_bf16 v[112:115], v[178:181], v[186:189], v[112:115]
	v_mfma_f32_16x16x32_bf16 v[100:103], v[170:173], v[194:197], v[100:103]
	v_mfma_f32_16x16x32_bf16 v[96:99], v[178:181], v[194:197], v[96:99]
	v_mfma_f32_16x16x32_bf16 v[84:87], v[170:173], v[214:217], v[84:87]
	v_mfma_f32_16x16x32_bf16 v[80:83], v[178:181], v[214:217], v[80:83]
	v_mfma_f32_16x16x32_bf16 v[68:71], v[170:173], v[222:225], v[68:71]
	v_mfma_f32_16x16x32_bf16 v[64:67], v[178:181], v[222:225], v[64:67]
	v_mfma_f32_16x16x32_bf16 v[242:245], v[166:169], v[138:141], v[242:245]
	v_mfma_f32_16x16x32_bf16 v[246:249], v[174:177], v[138:141], v[246:249]
	v_mfma_f32_16x16x32_bf16 v[242:245], v[170:173], v[250:253], v[242:245]
	v_mfma_f32_16x16x32_bf16 v[246:249], v[178:181], v[250:253], v[246:249]
	s_setprio 0
	s_barrier
	s_add_u32 s70, s66, 0x180
	s_addc_u32 s71, s67, 0
	s_mov_b32 exec_lo, 0xffff
	s_mov_b32 exec_hi, 0
	s_add_i32 m0, s68, 0x800
	s_nop 0
	global_load_lds_dwordx4 v254, s[70:71]
	s_mov_b64 exec, -1
	s_add_i32 s46, s62, s4
	v_lshl_add_u64 v[198:199], v[198:199], 0, s[24:25]
	s_mov_b32 m0, s46
	ds_read_b128 v[182:185], v157 offset:49152
	ds_read_b128 v[186:189], v157 offset:50176
	ds_read_b128 v[190:193], v157 offset:51200
	ds_read_b128 v[194:197], v157 offset:52224
	ds_read_b128 v[210:213], v157 offset:53248
	ds_read_b128 v[214:217], v157 offset:54272
	ds_read_b128 v[218:221], v157 offset:55296
	ds_read_b128 v[222:225], v157 offset:56320
	global_load_lds_dwordx4 v[198:199], off
	s_add_i32 m0, s46, 0x2000
	s_add_u32 s44, s44, 0x80080
	v_lshl_add_u64 v[198:199], v[226:227], 0, s[24:25]
	s_addc_u32 s45, s45, 0
	s_add_i32 s46, s63, s4
	global_load_lds_dwordx4 v[198:199], off
	v_lshl_add_u64 v[198:199], s[44:45], 0, v[128:129]
	s_mov_b32 m0, s46
	s_nop 0
	global_load_lds_dwordx4 v[198:199], off
	v_lshl_add_u64 v[198:199], s[44:45], 0, v[130:131]
	s_add_i32 m0, s46, 0x2000
	s_nop 0
	global_load_lds_dwordx4 v[198:199], off
	v_lshl_add_u64 v[198:199], v[228:229], 0, s[24:25]
	s_mov_b32 m0, s54
	s_nop 0
	global_load_lds_dwordx4 v[198:199], off
	v_lshl_add_u64 v[198:199], v[230:231], 0, s[24:25]
	s_mov_b32 m0, s55
	s_nop 0
	global_load_lds_dwordx4 v[198:199], off
	s_waitcnt vmcnt(9)
	s_waitcnt lgkmcnt(0)
	s_barrier
	s_setprio 1
	s_waitcnt lgkmcnt(0)
	v_mfma_f32_16x16x32_bf16 v[60:63], v[142:145], v[182:185], v[60:63]
	v_mfma_f32_16x16x32_bf16 v[56:59], v[158:161], v[182:185], v[56:59]
	v_mfma_f32_16x16x32_bf16 v[44:47], v[142:145], v[190:193], v[44:47]
	v_mfma_f32_16x16x32_bf16 v[40:43], v[158:161], v[190:193], v[40:43]
	v_mfma_f32_16x16x32_bf16 v[28:31], v[142:145], v[210:213], v[28:31]
	v_mfma_f32_16x16x32_bf16 v[24:27], v[158:161], v[210:213], v[24:27]
	v_mfma_f32_16x16x32_bf16 v[12:15], v[142:145], v[218:221], v[12:15]
	v_mfma_f32_16x16x32_bf16 v[8:11], v[158:161], v[218:221], v[8:11]
	v_mfma_f32_16x16x32_bf16 v[60:63], v[146:149], v[186:189], v[60:63]
	v_mfma_f32_16x16x32_bf16 v[56:59], v[162:165], v[186:189], v[56:59]
	v_mfma_f32_16x16x32_bf16 v[44:47], v[146:149], v[194:197], v[44:47]
	v_mfma_f32_16x16x32_bf16 v[40:43], v[162:165], v[194:197], v[40:43]
	v_mfma_f32_16x16x32_bf16 v[28:31], v[146:149], v[214:217], v[28:31]
	v_mfma_f32_16x16x32_bf16 v[24:27], v[162:165], v[214:217], v[24:27]
	v_mfma_f32_16x16x32_bf16 v[12:15], v[146:149], v[222:225], v[12:15]
	v_mfma_f32_16x16x32_bf16 v[8:11], v[162:165], v[222:225], v[8:11]
	s_setprio 0
	s_setprio 1
	v_mfma_f32_16x16x32_bf16 v[52:55], v[166:169], v[182:185], v[52:55]
	v_mfma_f32_16x16x32_bf16 v[48:51], v[174:177], v[182:185], v[48:51]
	v_mfma_f32_16x16x32_bf16 v[36:39], v[166:169], v[190:193], v[36:39]
	v_mfma_f32_16x16x32_bf16 v[32:35], v[174:177], v[190:193], v[32:35]
	v_mfma_f32_16x16x32_bf16 v[20:23], v[166:169], v[210:213], v[20:23]
	v_mfma_f32_16x16x32_bf16 v[16:19], v[174:177], v[210:213], v[16:19]
	v_mfma_f32_16x16x32_bf16 v[4:7], v[166:169], v[218:221], v[4:7]
	v_mfma_f32_16x16x32_bf16 v[0:3], v[174:177], v[218:221], v[0:3]
	v_mfma_f32_16x16x32_bf16 v[52:55], v[170:173], v[186:189], v[52:55]
	v_mfma_f32_16x16x32_bf16 v[48:51], v[178:181], v[186:189], v[48:51]
	v_mfma_f32_16x16x32_bf16 v[36:39], v[170:173], v[194:197], v[36:39]
	v_mfma_f32_16x16x32_bf16 v[32:35], v[178:181], v[194:197], v[32:35]
	v_mfma_f32_16x16x32_bf16 v[20:23], v[170:173], v[214:217], v[20:23]
	v_mfma_f32_16x16x32_bf16 v[16:19], v[178:181], v[214:217], v[16:19]
	v_mfma_f32_16x16x32_bf16 v[4:7], v[170:173], v[222:225], v[4:7]
	v_mfma_f32_16x16x32_bf16 v[0:3], v[178:181], v[222:225], v[0:3]
	s_setprio 0
	s_barrier
	s_add_i32 s61, s61, 2
	s_add_u32 s59, s59, 0x100
	s_addc_u32 s60, s60, 0
	s_add_u32 s42, s42, 0x100
	s_addc_u32 s43, s43, 0
	s_add_u32 s66, s66, 0x100
	s_addc_u32 s67, s67, 0
	s_cmp_gt_u32 s61, 29
	s_cbranch_scc0 .LBB0_299
	s_and_b64 vcc, exec, s[26:27]
	s_cbranch_vccz .LBB0_302
	s_barrier

.LBB0_353:
	s_cmp_lt_u32 s65, 4
	s_cbranch_scc0 .Lslab3_done
	s_and_b32 s70, s2, 7
	s_lshr_b32 s71, s2, 3
	s_lshl_b32 s70, s70, 3
	s_lshr_b32 s72, s71, 2
	s_add_i32 s70, s70, s72
	s_and_b32 s71, s71, 3
	s_lshl_b32 s72, s70, 4
	s_lshl_b32 s73, s71, 8
	s_lshl_b32 s74, s65, 5
	s_add_i32 s73, s73, s74
	s_lshl_b32 s74, s72, 12
	s_lshl_b32 s75, s73, 2
	s_add_u32 s74, s74, s75
	s_add_u32 s76, s14, s74
	s_addc_u32 s77, s15, 0
	s_add_u32 s74, s74, 0x4000000
	s_add_u32 s78, s18, s74
	s_addc_u32 s79, s19, 0
	s_lshl_b32 s74, s72, 11
	s_add_u32 s74, s74, 0x2000000
	s_lshl_b32 s75, s73, 1
	s_add_u32 s74, s74, s75
	s_add_u32 s80, s20, s74
	s_addc_u32 s81, s21, 0
	s_lshl_b32 s74, s72, 2
	s_add_u32 s74, s74, 0x10000
	s_add_u32 s82, s22, s74
	s_addc_u32 s83, s23, 0
	v_and_b32_e32 v0, 15, v200
	v_lshrrev_b32_e32 v1, 4, v200
	v_lshlrev_b32_e32 v2, 12, v0
	v_lshl_add_u32 v2, v1, 4, v2
	v_lshlrev_b32_e32 v3, 11, v0
	v_lshl_add_u32 v3, v1, 3, v3
	v_lshlrev_b32_e32 v0, 2, v0
	v_xor_b32_e32 v24, 16, v200
	v_lshlrev_b32_e32 v24, 2, v24
	v_xor_b32_e32 v25, 32, v200
	v_lshlrev_b32_e32 v25, 2, v25
	global_load_dwordx4 v[4:7], v2, s[76:77]
	global_load_dwordx4 v[8:11], v2, s[76:77] offset:64
	global_load_dwordx4 v[12:15], v2, s[76:77] offset:512
	global_load_dwordx4 v[16:19], v2, s[76:77] offset:576
	s_waitcnt vmcnt(0)
	v_pk_add_f32 v[4:5], v[4:5], v[234:235]
	v_pk_add_f32 v[6:7], v[6:7], v[236:237]
	v_pk_add_f32 v[8:9], v[8:9], v[238:239]
	v_pk_add_f32 v[10:11], v[10:11], v[240:241]
	v_pk_add_f32 v[12:13], v[12:13], v[242:243]
	v_pk_add_f32 v[14:15], v[14:15], v[244:245]
	v_pk_add_f32 v[16:17], v[16:17], v[246:247]
	v_pk_add_f32 v[18:19], v[18:19], v[248:249]
	global_store_dwordx4 v2, v[4:7], s[78:79]
	v_cvt_pk_bf16_f32 v20, v4, v5
	v_cvt_pk_bf16_f32 v21, v6, v7
	global_store_dwordx2 v3, v[20:21], s[80:81]
	v_mul_f32_e32 v22, v4, v4
	v_fmac_f32_e32 v22, v5, v5
	v_mul_f32_e32 v23, v6, v6
	v_fmac_f32_e32 v23, v7, v7
	v_add_f32_e32 v22, v22, v23
	v_mov_b32_e32 v26, v22
	global_store_dwordx4 v2, v[8:11], s[78:79] offset:64
	v_cvt_pk_bf16_f32 v20, v8, v9
	v_cvt_pk_bf16_f32 v21, v10, v11
	global_store_dwordx2 v3, v[20:21], s[80:81] offset:32
	v_mul_f32_e32 v22, v8, v8
	v_fmac_f32_e32 v22, v9, v9
	v_mul_f32_e32 v23, v10, v10
	v_fmac_f32_e32 v23, v11, v11
	v_add_f32_e32 v22, v22, v23
	v_add_f32_e32 v26, v26, v22
	global_store_dwordx4 v2, v[12:15], s[78:79] offset:512
	v_cvt_pk_bf16_f32 v20, v12, v13
	v_cvt_pk_bf16_f32 v21, v14, v15
	global_store_dwordx2 v3, v[20:21], s[80:81] offset:256
	v_mul_f32_e32 v22, v12, v12
	v_fmac_f32_e32 v22, v13, v13
	v_mul_f32_e32 v23, v14, v14
	v_fmac_f32_e32 v23, v15, v15
	v_add_f32_e32 v22, v22, v23
	v_add_f32_e32 v26, v26, v22
	global_store_dwordx4 v2, v[16:19], s[78:79] offset:576
	v_cvt_pk_bf16_f32 v20, v16, v17
	v_cvt_pk_bf16_f32 v21, v18, v19
	global_store_dwordx2 v3, v[20:21], s[80:81] offset:288
	v_mul_f32_e32 v22, v16, v16
	v_fmac_f32_e32 v22, v17, v17
	v_mul_f32_e32 v23, v18, v18
	v_fmac_f32_e32 v23, v19, v19
	v_add_f32_e32 v22, v22, v23
	v_add_f32_e32 v26, v26, v22
	ds_bpermute_b32 v22, v24, v26
	s_waitcnt lgkmcnt(0)
	v_add_f32_e32 v26, v26, v22
	ds_bpermute_b32 v22, v25, v26
	s_waitcnt lgkmcnt(0)
	v_add_f32_e32 v26, v26, v22
	s_mov_b32 exec_lo, 0xffff
	s_mov_b32 exec_hi, 0
	global_atomic_add_f32 v0, v26, s[82:83]
	s_mov_b64 exec, -1

.LBB0_354:
	s_mov_b32 s98, 1
	s_branch .Lp0_entry
